# static s_setprio 1 for the second 4-wave group during the attention phase (on top of wait fixes + firstwait)
# baseline (speedup 1.0000x reference)
; DEV void attn_unit(const Params& P, int b, int qb, int h) {
;     ...
;   float* suf = (float*)(smem + AT_SUF) + g * 128;
;   __syncthreads();
;   {
;     const float* offt = (const float*)(smem + AT_OFF) + (b * 8 + h) * 128;
;     if (gt < 128) suf[gt] = (gt < qb) ? (offt[qb] - offt[gt]) : 0.f;
; __global__ void __launch_bounds__(512) mega(Params P) {
;     ...
;       const int u = hs[8];
;       if (u >= 2048) break;
;       const int qb = 127 - (u >> 4), bh = u & 15, b = bh >> 3;
;       const int hh = hs[7 - (bh & 7)];
.LBB0_159:
	s_or_b64 exec, exec, s[6:7]
	s_waitcnt lgkmcnt(0)
	s_barrier
	ds_read_b32 v0, v127
	s_mov_b64 s[6:7], -1
	s_waitcnt lgkmcnt(0)
	v_cmp_lt_i32_e32 vcc, s5, v0
	v_readfirstlane_b32 s8, v0
	s_cbranch_vccnz .LBB0_154
	s_andn2_b32 s6, 7, s8
	s_lshl_b32 s6, s6, 2
	s_add_i32 s6, s6, 0
	s_add_i32 s6, s6, 0x23c40
	v_mov_b32_e32 v0, s6
	ds_read_b32 v1, v0
	s_bfe_u32 s2, s8, 0x10003
	v_mov_b32_e32 v119, v176
	s_ashr_i32 s24, s8, 4
	s_lshl_b32 s6, s2, 3
	v_ashrrev_i32_e32 v129, 8, v119
	v_and_b32_e32 v131, 0xff, v119
	v_readfirstlane_b32 s99, v129
	s_cmp_lg_u32 s99, 0
	s_cbranch_scc0 .Lattn_prio_skip
	s_setprio 1
.Lattn_prio_skip:
	s_waitcnt lgkmcnt(0)
	v_readfirstlane_b32 s7, v1
	s_sub_i32 s40, 0x7f, s24
	s_add_i32 s10, s7, s6
	v_lshl_add_u32 v132, v129, 9, s37
	v_cmp_gt_u32_e64 s[6:7], s28, v131
	s_barrier
	s_and_saveexec_b64 s[8:9], s[6:7]
	s_cbranch_execz .LBB0_164
	v_cmp_gt_u32_e32 vcc, s40, v131
	v_mov_b32_e32 v0, 0
	s_and_saveexec_b64 s[12:13], vcc
	s_cbranch_execz .LBB0_163
	s_lshl_b32 s11, s10, 9
	s_add_i32 s11, s11, 0
	s_add_i32 s11, s11, 0x23d00
	s_lshl_b32 s20, s24, 2
	s_sub_i32 s20, s11, s20
	v_lshl_add_u32 v0, v131, 2, s11
	v_mov_b32_e32 v2, s20
	ds_read_b32 v2, v2 offset:508
	ds_read_b32 v0, v0
	s_waitcnt lgkmcnt(0)
	v_sub_f32_e32 v0, v2, v0

; __global__ void __launch_bounds__(512) mega(Params P) {
;     ...
;     unsigned* ctr2 = ctr + 16;
; #pragma nounroll
;     for (;;) {
;       __syncthreads();
;       if (tid == 0) hs[8] = (int)atomicAdd(ctr2, 1u);
;       __syncthreads();
;       const int c = hs[8];
;       if (c >= 2560) break;
;       if (c < 2048) {
;         const int t = c >> 9; const size_t off = (size_t)(c & 511) * 32768;
;         const float* src = ((t & 1) ? P.peer_v : P.peer_u) + (size_t)(t >> 1) * 16384 * 1024 + off;
;         unsigned char* dst = ws + WS_TAB + (size_t)t * 16 * MB + off;
.LBB0_197:
	s_setprio 0
	s_add_u32 s0, s82, 0x110040
	s_addc_u32 s1, s83, 0
	s_add_u32 s22, s82, 0xac00000
	s_addc_u32 s23, s83, 0
	s_add_u32 s24, s82, 0x2c00000
	s_addc_u32 s25, s83, 0
	v_or_b32_e32 v0, 0x2000, v180
	v_mov_b32_e32 v1, 0
	v_or_b32_e32 v12, 0x4000, v180
	v_or_b32_e32 v14, 0x6000, v180
	s_add_i32 s29, 0, 0x23c60
	s_movk_i32 s26, 0x2000
	s_movk_i32 s27, 0x4000
	s_movk_i32 s28, 0x6000
	v_mov_b32_e32 v179, v1
	v_or_b32_e32 v2, 0x4000, v178
	v_mov_b32_e32 v3, v1
	s_mov_b32 s3, 0
	v_mov_b32_e32 v8, s29
	s_movk_i32 s30, 0x9ff
	v_lshlrev_b32_e32 v4, 2, v180
	v_lshlrev_b32_e32 v6, 1, v180
	s_mov_b64 s[4:5], 0x4000
	v_lshlrev_b32_e32 v9, 2, v0
	v_lshlrev_b32_e32 v10, 1, v0
	s_mov_b64 s[6:7], 0xc000
	s_mov_b32 s31, 0xc000
	v_lshlrev_b32_e32 v11, 2, v12
	v_lshlrev_b32_e32 v12, 1, v12
	s_mov_b64 s[8:9], 0x14000
	s_mov_b32 s33, 0x14000
	s_mov_b32 s34, 0xa000
	v_lshlrev_b32_e32 v13, 2, v14
	v_lshlrev_b32_e32 v14, 1, v14
	s_mov_b64 s[10:11], 0x1c000
	s_mov_b32 s35, 0x1c000
	s_mov_b64 s[12:13], 0x8000
	s_mov_b32 s60, 0x8000
	s_mov_b64 s[14:15], 0x18000
	s_mov_b32 s61, 0x18000
	s_branch .LBB0_200
